# attention-cache bf16 conversion moved from the 16 converter workgroups (per-CU bandwidth bound critical path) to the tail of the 240 GEMM workgroups in the in-projection phase
# speedup vs baseline: 1.0313x; 1.0161x over previous
.LBB0_285:
	s_and_b64 vcc, exec, s[34:35]
	s_cbranch_vccz .Lmy_cc2_skip
	v_lshl_add_u32 v50, s2, 9, v154
	s_mov_b64 s[30:31], s[0:1]
	s_mov_b64 s[34:35], s[0:1]
	s_load_dwordx2 s[30:31], s[30:31], 0x20
	s_nop 0
	s_load_dwordx2 s[34:35], s[34:35], 0x28
	s_lshl_b32 s4, s18, 23
	v_mov_b32_e32 v51, 0
	s_waitcnt lgkmcnt(0)
	s_add_u32 s30, s30, s4
	s_addc_u32 s31, s31, 0
	s_add_u32 s34, s34, s4
	s_addc_u32 s35, s35, 0
	v_mov_b32_e32 v40, s30
	v_mov_b32_e32 v41, s31
	v_mov_b32_e32 v42, s34
	v_mov_b32_e32 v43, s35
	v_lshl_add_u64 v[44:45], v[50:51], 4, s[20:21]
	s_mov_b64 s[4:5], 0x79e0000
	v_lshl_add_u64 v[44:45], v[44:45], 0, s[4:5]
	v_add_u32_e32 v46, 0x78000, v50
	s_mov_b32 s6, 0x80000
	v_cmp_gt_i32_e64 s[22:23], s6, v46
	s_mov_b64 s[36:37], exec
	v_add_u32_e32 v46, 0x0, v50
	v_add_u32_e32 v47, 0xfffc0000, v46
	v_cmp_lt_i32_e32 vcc, 0x3ffff, v46
	s_nop 1
	v_cndmask_b32_e32 v47, v46, v47, vcc
	v_cndmask_b32_e32 v49, v41, v43, vcc
	v_cndmask_b32_e32 v48, v40, v42, vcc
	v_lshlrev_b32_e32 v47, 5, v47
	v_add_co_u32_e32 v48, vcc, v48, v47
	s_nop 1
	v_addc_co_u32_e32 v49, vcc, 0, v49, vcc
	global_load_dwordx4 v[0:3], v[48:49], off nt
	global_load_dwordx4 v[4:7], v[48:49], off offset:16 nt
	v_add_u32_e32 v46, 0x1e000, v50
	v_add_u32_e32 v47, 0xfffc0000, v46
	v_cmp_lt_i32_e32 vcc, 0x3ffff, v46
	s_nop 1
	v_cndmask_b32_e32 v47, v46, v47, vcc
	v_cndmask_b32_e32 v49, v41, v43, vcc
	v_cndmask_b32_e32 v48, v40, v42, vcc
	v_lshlrev_b32_e32 v47, 5, v47
	v_add_co_u32_e32 v48, vcc, v48, v47
	s_nop 1
	v_addc_co_u32_e32 v49, vcc, 0, v49, vcc
	global_load_dwordx4 v[8:11], v[48:49], off nt
	global_load_dwordx4 v[12:15], v[48:49], off offset:16 nt
	v_add_u32_e32 v46, 0x3c000, v50
	v_add_u32_e32 v47, 0xfffc0000, v46
	v_cmp_lt_i32_e32 vcc, 0x3ffff, v46
	s_nop 1
	v_cndmask_b32_e32 v47, v46, v47, vcc
	v_cndmask_b32_e32 v49, v41, v43, vcc
	v_cndmask_b32_e32 v48, v40, v42, vcc
	v_lshlrev_b32_e32 v47, 5, v47
	v_add_co_u32_e32 v48, vcc, v48, v47
	s_nop 1
	v_addc_co_u32_e32 v49, vcc, 0, v49, vcc
	global_load_dwordx4 v[16:19], v[48:49], off nt
	global_load_dwordx4 v[20:23], v[48:49], off offset:16 nt
	v_add_u32_e32 v46, 0x5a000, v50
	v_add_u32_e32 v47, 0xfffc0000, v46
	v_cmp_lt_i32_e32 vcc, 0x3ffff, v46
	s_nop 1
	v_cndmask_b32_e32 v47, v46, v47, vcc
	v_cndmask_b32_e32 v49, v41, v43, vcc
	v_cndmask_b32_e32 v48, v40, v42, vcc
	v_lshlrev_b32_e32 v47, 5, v47
	v_add_co_u32_e32 v48, vcc, v48, v47
	s_nop 1
	v_addc_co_u32_e32 v49, vcc, 0, v49, vcc
	global_load_dwordx4 v[24:27], v[48:49], off nt
	global_load_dwordx4 v[28:31], v[48:49], off offset:16 nt
	v_add_u32_e32 v46, 0x78000, v50
	v_min_i32_e32 v46, 0x7ffff, v46
	v_add_u32_e32 v47, 0xfffc0000, v46
	v_cmp_lt_i32_e32 vcc, 0x3ffff, v46
	s_nop 1
	v_cndmask_b32_e32 v47, v46, v47, vcc
	v_cndmask_b32_e32 v49, v41, v43, vcc
	v_cndmask_b32_e32 v48, v40, v42, vcc
	v_lshlrev_b32_e32 v47, 5, v47
	v_add_co_u32_e32 v48, vcc, v48, v47
	s_nop 1
	v_addc_co_u32_e32 v49, vcc, 0, v49, vcc
	global_load_dwordx4 v[32:35], v[48:49], off nt
	global_load_dwordx4 v[36:39], v[48:49], off offset:16 nt
	s_waitcnt vmcnt(8)
	v_cvt_pk_bf16_f32 v0, v0, v1
	v_cvt_pk_bf16_f32 v1, v2, v3
	v_cvt_pk_bf16_f32 v2, v4, v5
	v_cvt_pk_bf16_f32 v3, v6, v7
	v_add_co_u32_e32 v52, vcc, 0x0, v44
	s_nop 1
	v_addc_co_u32_e32 v53, vcc, 0, v45, vcc
	global_store_dwordx4 v[52:53], v[0:3], off
	s_waitcnt vmcnt(7)
	v_cvt_pk_bf16_f32 v8, v8, v9
	v_cvt_pk_bf16_f32 v9, v10, v11
	v_cvt_pk_bf16_f32 v10, v12, v13
	v_cvt_pk_bf16_f32 v11, v14, v15
	v_add_co_u32_e32 v52, vcc, 0x1e0000, v44
	s_nop 1
	v_addc_co_u32_e32 v53, vcc, 0, v45, vcc
	global_store_dwordx4 v[52:53], v[8:11], off
	s_waitcnt vmcnt(6)
	v_cvt_pk_bf16_f32 v16, v16, v17
	v_cvt_pk_bf16_f32 v17, v18, v19
	v_cvt_pk_bf16_f32 v18, v20, v21
	v_cvt_pk_bf16_f32 v19, v22, v23
	v_add_co_u32_e32 v52, vcc, 0x3c0000, v44
	s_nop 1
	v_addc_co_u32_e32 v53, vcc, 0, v45, vcc
	global_store_dwordx4 v[52:53], v[16:19], off
	s_waitcnt vmcnt(5)
	v_cvt_pk_bf16_f32 v24, v24, v25
	v_cvt_pk_bf16_f32 v25, v26, v27
	v_cvt_pk_bf16_f32 v26, v28, v29
	v_cvt_pk_bf16_f32 v27, v30, v31
	v_add_co_u32_e32 v52, vcc, 0x5a0000, v44
	s_nop 1
	v_addc_co_u32_e32 v53, vcc, 0, v45, vcc
	global_store_dwordx4 v[52:53], v[24:27], off
	s_and_b64 exec, exec, s[22:23]
	s_cbranch_execz .Lmy_cc2_done
	s_waitcnt vmcnt(4)
	v_cvt_pk_bf16_f32 v32, v32, v33
	v_cvt_pk_bf16_f32 v33, v34, v35
	v_cvt_pk_bf16_f32 v34, v36, v37
	v_cvt_pk_bf16_f32 v35, v38, v39
	v_add_co_u32_e32 v52, vcc, 0x780000, v44
	s_nop 1
	v_addc_co_u32_e32 v53, vcc, 0, v45, vcc
	global_store_dwordx4 v[52:53], v[32:35], off
.Lmy_cc2_done:
	s_mov_b64 exec, s[36:37]
	s_branch .LBB0_290

.LBB0_301:
.LBB0_304:
.LBB0_305:
	v_readlane_b32 s4, v254, 7
	v_readlane_b32 s5, v254, 8
	s_waitcnt vmcnt(0)
	s_andn2_b64 vcc, exec, s[4:5]
	s_waitcnt lgkmcnt(0)
	v_cndmask_b32_e64 v0, 0, 1, s[4:5]
	v_cmp_ne_u32_e64 s[6:7], 1, v0
	s_barrier
	s_nop 0
	v_writelane_b32 v255, s6, 42
	s_nop 1
	v_writelane_b32 v255, s7, 43
	s_cbranch_vccnz .LBB0_359
	v_mbcnt_lo_u32_b32 v0, -1, 0
	v_mbcnt_hi_u32_b32 v0, -1, v0
	s_nop 0
	v_cmp_eq_u32_e32 vcc, 0, v0
	s_and_saveexec_b64 s[20:21], vcc
	s_cbranch_execz .LBB0_358
	v_readlane_b32 s2, v255, 32
	s_waitcnt vmcnt(0) expcnt(0) lgkmcnt(0)
	s_nop 0
	v_mov_b32_e32 v0, s2
	ds_read_b32 v2, v0
	v_readlane_b32 s2, v255, 33
	s_waitcnt lgkmcnt(0)
	v_cmp_ne_u32_e32 vcc, 0, v2
	v_mov_b32_e32 v0, s2
	ds_read_b32 v0, v0
	s_cbranch_vccnz .LBB0_322
	s_mov_b32 s2, 1
	s_branch .LBB0_310
